# merge phase: all 17 loads of an iteration issued at the top (one memory round trip per iteration instead of four serial ones); staging regs v100-v143
# baseline (speedup 1.0000x reference)
; __device__ void merge_phase(const Params& p) {
;     ...
;         { const int hh = lane >> 4, sub = lane & 15;
;           const bf16_t* src = og + (size_t)tok * 1024 + hh * 256 + sub * 16;
;           const u32x4 a = *(const u32x4*)src, b = *(const u32x4*)(src + 8);
;           float xv[16];
; #pragma unroll
;           for (int j = 0; j < 4; ++j) { xv[2 * j] = bflo(a[j]); xv[2 * j + 1] = bfhi(a[j]); xv[8 + 2 * j] = bflo(b[j]); xv[8 + 2 * j + 1] = bfhi(b[j]); }
;           float s = 0.f;
; #pragma unroll
;           for (int j = 0; j < 16; ++j) s += xv[j];
;           s += __shfl_xor(s, 1); s += __shfl_xor(s, 2); s += __shfl_xor(s, 4); s += __shfl_xor(s, 8);
;           const float mean = s * (1.0f / 256.0f);
;           float q = 0.f;
; #pragma unroll
;           for (int j = 0; j < 16; ++j) { const float dlt = xv[j] - mean; q += dlt * dlt; }
;           q += __shfl_xor(q, 1); q += __shfl_xor(q, 2); q += __shfl_xor(q, 4); q += __shfl_xor(q, 8);
;           const float rstd = rsqrtf(q * (1.0f / 256.0f) + 1e-5f);
;           const bf16_t* rgp = h + (size_t)tok * HC + 2048 + hh * 256 + sub * 16;
;           const u32x4 ra = *(const u32x4*)rgp, rb = *(const u32x4*)(rgp + 8);
;           const float* ngp = p.norm_g + hh * 256 + sub * 16;
;           float ov[16];
; #pragma unroll
;           for (int j4 = 0; j4 < 4; ++j4) { const f32x4 ng = *(const f32x4*)(ngp + 4 * j4);
; #pragma unroll
;               for (int j = 0; j < 4; ++j) { const int e = 4 * j4 + j; const unsigned rw = (e < 8) ? ra[e >> 1] : rb[(e - 8) >> 1]; const float rv = (e & 1) ? bfhi(rw) : bflo(rw);
;                   ov[e] = (xv[e] - mean) * rstd * ng[j] * silu_f(rv); } }
;     ...
;           const float l0 = lse[(size_t)tok * 8 + hd], l1 = lse[(size_t)T_TOK * 8 + (size_t)tok * 8 + hd], l2 = lse[(size_t)2 * T_TOK * 8 + (size_t)tok * 8 + hd];
;           const float m = fmaxf(l0, fmaxf(l1, l2));
;           float e0 = fexp2((l0 - m) * LOG2E), e1 = fexp2((l1 - m) * LOG2E), e2 = fexp2((l2 - m) * LOG2E);
;           const float inv = 1.0f / (e0 + e1 + e2); e0 *= inv; e1 *= inv; e2 *= inv;
;           const size_t so = (size_t)tok * 1024 + hd * 128 + sub * 16;
;           u32x4 o[2];
; #pragma unroll
;           for (int hf = 0; hf < 2; ++hf) { const u32x4 a = *(const u32x4*)(od0 + so + 8 * hf), b = *(const u32x4*)(od1 + so + 8 * hf), c = *(const u32x4*)(od2 + so + 8 * hf);
.LBB0_100:
	v_ashrrev_i32_e32 v1, 31, v0
	v_lshlrev_b64 v[50:51], 11, v[0:1]
	v_lshl_add_u64 v[4:5], v[36:37], 0, v[50:51]
	global_load_dwordx4 v[24:27], v[4:5], off nt
	global_load_dwordx4 v[32:35], v[4:5], off offset:16 nt
	v_mov_b64_e32 v[4:5], s[92:93]
	v_mad_i64_i32 v[52:53], s[6:7], v0, s48, v[4:5]
	v_lshl_add_u64 v[4:5], v[52:53], 0, v[2:3]
	v_mov_b32_e32 v41, v3
	v_lshl_add_u64 v[4:5], v[4:5], 0, v[40:41]
	s_mov_b64 s[6:7], 0xd101000
	v_lshl_add_u64 v[6:7], v[4:5], 0, s[6:7]
	s_mov_b32 s6, 0xd101000
	v_add_co_u32_e32 v4, vcc, s6, v4
	s_nop 1
	v_addc_co_u32_e32 v5, vcc, 0, v5, vcc
	global_load_dwordx4 v[28:31], v[4:5], off nt
	s_nop 0
	global_load_dwordx4 v[4:7], v[6:7], off offset:16 nt
	s_nop 0
	global_load_dwordx4 v[8:11], v[38:39], off offset:48
	global_load_dwordx4 v[12:15], v[38:39], off offset:32
	global_load_dwordx4 v[20:23], v[38:39], off
	global_load_dwordx4 v[16:19], v[38:39], off offset:16
	v_lshlrev_b64 v[128:129], 5, v[0:1]
	v_mov_b32_e32 v142, v42
	v_mov_b32_e32 v143, v3
	v_lshl_add_u64 v[128:129], s[12:13], 0, v[128:129]
	v_lshl_add_u64 v[128:129], v[128:129], 0, v[142:143]
	v_add_co_u32_e32 v130, vcc, s9, v128
	s_nop 1
	v_addc_co_u32_e32 v131, vcc, 0, v129, vcc
	global_load_dword v100, v[128:129], off nt
	global_load_dword v101, v[130:131], off nt
	v_add_co_u32_e32 v132, vcc, 0x100000, v128
	s_nop 1
	v_addc_co_u32_e32 v133, vcc, 0, v129, vcc
	global_load_dword v102, v[132:133], off nt
	v_or_b32_e32 v135, v51, v45
	v_or_b32_e32 v134, v50, v44
	v_lshl_add_u64 v[136:137], s[54:55], 0, v[134:135]
	v_lshl_add_u64 v[138:139], s[10:11], 0, v[134:135]
	v_lshl_add_u64 v[140:141], s[24:25], 0, v[134:135]
	global_load_dwordx4 v[104:107], v[136:137], off offset:16 nt
	global_load_dwordx4 v[108:111], v[136:137], off nt
	global_load_dwordx4 v[112:115], v[138:139], off offset:16 nt
	global_load_dwordx4 v[116:119], v[138:139], off nt
	global_load_dwordx4 v[120:123], v[140:141], off offset:16 nt
	global_load_dwordx4 v[124:127], v[140:141], off nt
	s_waitcnt vmcnt(15)
	v_lshlrev_b32_e32 v58, 16, v27
	v_and_b32_e32 v59, 0xffff0000, v27
	v_lshlrev_b32_e32 v56, 16, v35
	v_and_b32_e32 v57, 0xffff0000, v35
	v_and_b32_e32 v61, 0xffff0000, v34
	v_and_b32_e32 v63, 0xffff0000, v26
	v_and_b32_e32 v65, 0xffff0000, v33
	v_lshlrev_b32_e32 v68, 16, v25
	v_and_b32_e32 v69, 0xffff0000, v25
	v_lshlrev_b32_e32 v70, 16, v32
	v_and_b32_e32 v71, 0xffff0000, v32
	s_waitcnt vmcnt(9)
	v_lshlrev_b32_e32 v27, 16, v31
	v_and_b32_e32 v31, 0xffff0000, v31
	v_mul_f32_e32 v35, 0xbfb8aa3b, v27
	v_exp_f32_e32 v54, v35
	v_mul_f32_e32 v35, 0xbfb8aa3b, v31
	v_exp_f32_e32 v55, v35
	s_nop 0
	v_pk_add_f32 v[54:55], v[54:55], 1.0 op_sel_hi:[1,0]
	s_nop 0
	v_div_scale_f32 v35, s[6:7], v55, v55, v31
	v_rcp_f32_e32 v43, v35
	s_nop 0
	v_fma_f32 v47, -v35, v43, 1.0
	v_fmac_f32_e32 v43, v47, v43
	v_div_scale_f32 v47, vcc, v31, v55, v31
	v_mul_f32_e32 v49, v47, v43
	v_fma_f32 v60, -v35, v49, v47
	v_fmac_f32_e32 v49, v60, v43
	v_fma_f32 v35, -v35, v49, v47
	v_div_fmas_f32 v35, v35, v43, v49
	v_div_fixup_f32 v55, v35, v55, v31
	v_div_scale_f32 v31, s[6:7], v54, v54, v27
	v_rcp_f32_e32 v35, v31
	v_lshlrev_b32_e32 v60, 16, v34
	v_fma_f32 v43, -v31, v35, 1.0
	v_fmac_f32_e32 v35, v43, v35
	v_div_scale_f32 v43, vcc, v27, v54, v27
	v_mul_f32_e32 v47, v43, v35
	v_fma_f32 v49, -v31, v47, v43
	v_fmac_f32_e32 v47, v49, v35
	v_fma_f32 v31, -v31, v47, v43
	v_div_fmas_f32 v31, v31, v35, v47
	v_div_fixup_f32 v54, v31, v54, v27
	v_lshlrev_b32_e32 v27, 16, v6
	v_and_b32_e32 v6, 0xffff0000, v6
	v_mul_f32_e32 v31, 0xbfb8aa3b, v27
	v_exp_f32_e32 v34, v31
	v_mul_f32_e32 v31, 0xbfb8aa3b, v6
	v_exp_f32_e32 v35, v31
	s_nop 0
	v_pk_add_f32 v[34:35], v[34:35], 1.0 op_sel_hi:[1,0]
	s_nop 0
	v_div_scale_f32 v31, s[6:7], v35, v35, v6
	v_rcp_f32_e32 v43, v31
	s_nop 0
	v_fma_f32 v47, -v31, v43, 1.0
	v_fmac_f32_e32 v43, v47, v43
	v_div_scale_f32 v47, vcc, v6, v35, v6
	v_mul_f32_e32 v49, v47, v43
	v_fma_f32 v62, -v31, v49, v47
	v_fmac_f32_e32 v49, v62, v43
	v_fma_f32 v31, -v31, v49, v47
	v_div_fmas_f32 v31, v31, v43, v49
	v_div_fixup_f32 v35, v31, v35, v6
	v_div_scale_f32 v6, s[6:7], v34, v34, v27
	v_rcp_f32_e32 v31, v6
	v_lshlrev_b32_e32 v62, 16, v26
	v_fma_f32 v43, -v6, v31, 1.0
	v_fmac_f32_e32 v31, v43, v31
	v_div_scale_f32 v43, vcc, v27, v34, v27
	v_mul_f32_e32 v47, v43, v31
	v_fma_f32 v49, -v6, v47, v43
	v_fmac_f32_e32 v47, v49, v31
	v_fma_f32 v6, -v6, v47, v43
	v_div_fmas_f32 v6, v6, v31, v47
	v_div_fixup_f32 v34, v6, v34, v27
	v_lshlrev_b32_e32 v6, 16, v30
	v_and_b32_e32 v30, 0xffff0000, v30
	v_mul_f32_e32 v26, 0xbfb8aa3b, v6
	v_mul_f32_e32 v27, 0xbfb8aa3b, v30
	v_exp_f32_e32 v26, v26
	v_exp_f32_e32 v27, v27
	s_nop 0
	v_pk_add_f32 v[26:27], v[26:27], 1.0 op_sel_hi:[1,0]
	s_nop 0
	v_div_scale_f32 v31, s[6:7], v27, v27, v30
	v_rcp_f32_e32 v43, v31
	s_nop 0
	v_fma_f32 v47, -v31, v43, 1.0
	v_fmac_f32_e32 v43, v47, v43
	v_div_scale_f32 v47, vcc, v30, v27, v30
	v_mul_f32_e32 v49, v47, v43
	v_fma_f32 v64, -v31, v49, v47
	v_fmac_f32_e32 v49, v64, v43
	v_fma_f32 v31, -v31, v49, v47
	v_div_fmas_f32 v31, v31, v43, v49
	v_div_fixup_f32 v27, v31, v27, v30
	v_div_scale_f32 v30, s[6:7], v26, v26, v6
	v_rcp_f32_e32 v31, v30
	v_lshlrev_b32_e32 v64, 16, v33
	v_fma_f32 v43, -v30, v31, 1.0
	v_fmac_f32_e32 v31, v43, v31
	v_div_scale_f32 v43, vcc, v6, v26, v6
	v_mul_f32_e32 v47, v43, v31
	v_fma_f32 v49, -v30, v47, v43
	v_fmac_f32_e32 v47, v49, v31
	v_fma_f32 v30, -v30, v47, v43
	v_div_fmas_f32 v30, v30, v31, v47
	v_div_fixup_f32 v26, v30, v26, v6
	v_lshlrev_b32_e32 v6, 16, v5
	v_and_b32_e32 v5, 0xffff0000, v5
	v_mul_f32_e32 v30, 0xbfb8aa3b, v6
	v_mul_f32_e32 v31, 0xbfb8aa3b, v5
	v_exp_f32_e32 v30, v30
	v_exp_f32_e32 v31, v31
; __device__ __forceinline__ float bflo(unsigned u) { return __uint_as_float(u << 16); }
; __device__ __forceinline__ float bfhi(unsigned u) { return __uint_as_float(u & 0xffff0000u); }
; __device__ __forceinline__ float silu_f(float v) { return v / (1.0f + fexp2(-v * LOG2E)); }
; __device__ void merge_phase(const Params& p) {
;     ...
;           float s = 0.f;
; #pragma unroll
;           for (int j = 0; j < 16; ++j) s += xv[j];
;           s += __shfl_xor(s, 1); s += __shfl_xor(s, 2); s += __shfl_xor(s, 4); s += __shfl_xor(s, 8);
;           const float mean = s * (1.0f / 256.0f);
;           float q = 0.f;
; #pragma unroll
;           for (int j = 0; j < 16; ++j) { const float dlt = xv[j] - mean; q += dlt * dlt; }
;           q += __shfl_xor(q, 1); q += __shfl_xor(q, 2); q += __shfl_xor(q, 4); q += __shfl_xor(q, 8);
;           const float rstd = rsqrtf(q * (1.0f / 256.0f) + 1e-5f);
;           const bf16_t* rgp = h + (size_t)tok * HC + 2048 + hh * 256 + sub * 16;
;           const u32x4 ra = *(const u32x4*)rgp, rb = *(const u32x4*)(rgp + 8);
;           const float* ngp = p.norm_g + hh * 256 + sub * 16;
;           float ov[16];
; #pragma unroll
;           for (int j4 = 0; j4 < 4; ++j4) { const f32x4 ng = *(const f32x4*)(ngp + 4 * j4);
; #pragma unroll
;               for (int j = 0; j < 4; ++j) { const int e = 4 * j4 + j; const unsigned rw = (e < 8) ? ra[e >> 1] : rb[(e - 8) >> 1]; const float rv = (e & 1) ? bfhi(rw) : bflo(rw);
;                   ov[e] = (xv[e] - mean) * rstd * ng[j] * silu_f(rv); } }
	s_nop 0
	v_pk_add_f32 v[30:31], v[30:31], 1.0 op_sel_hi:[1,0]
	s_nop 0
	v_div_scale_f32 v33, s[6:7], v31, v31, v5
	v_rcp_f32_e32 v43, v33
	s_nop 0
	v_fma_f32 v47, -v33, v43, 1.0
	v_fmac_f32_e32 v43, v47, v43
	v_div_scale_f32 v47, vcc, v5, v31, v5
	v_mul_f32_e32 v49, v47, v43
	v_fma_f32 v66, -v33, v49, v47
	v_fmac_f32_e32 v49, v66, v43
	v_fma_f32 v33, -v33, v49, v47
	v_div_fmas_f32 v33, v33, v43, v49
	v_div_fixup_f32 v31, v33, v31, v5
	v_div_scale_f32 v5, s[6:7], v30, v30, v6
	v_rcp_f32_e32 v33, v5
	s_nop 0
	v_fma_f32 v43, -v5, v33, 1.0
	v_fmac_f32_e32 v33, v43, v33
	v_div_scale_f32 v43, vcc, v6, v30, v6
	v_mul_f32_e32 v47, v43, v33
	v_fma_f32 v49, -v5, v47, v43
	v_fmac_f32_e32 v47, v49, v33
	v_fma_f32 v5, -v5, v47, v43
	v_div_fmas_f32 v5, v5, v33, v47
	v_div_fixup_f32 v30, v5, v30, v6
	v_lshlrev_b32_e32 v5, 16, v29
	v_and_b32_e32 v6, 0xffff0000, v29
	v_mul_f32_e32 v25, 0xbfb8aa3b, v5
	v_exp_f32_e32 v66, v25
	v_mul_f32_e32 v25, 0xbfb8aa3b, v6
	v_exp_f32_e32 v67, v25
	s_nop 0
	v_pk_add_f32 v[66:67], v[66:67], 1.0 op_sel_hi:[1,0]
	s_nop 0
	v_div_scale_f32 v25, s[6:7], v67, v67, v6
	v_rcp_f32_e32 v29, v25
	s_nop 0
	v_fma_f32 v33, -v25, v29, 1.0
	v_fmac_f32_e32 v29, v33, v29
	v_div_scale_f32 v33, vcc, v6, v67, v6
	v_mul_f32_e32 v43, v33, v29
	v_fma_f32 v47, -v25, v43, v33
	v_fmac_f32_e32 v43, v47, v29
	v_fma_f32 v25, -v25, v43, v33
	v_div_fmas_f32 v25, v25, v29, v43
	v_div_fixup_f32 v67, v25, v67, v6
	v_div_scale_f32 v6, s[6:7], v66, v66, v5
	v_rcp_f32_e32 v25, v6
	s_nop 0
	v_fma_f32 v29, -v6, v25, 1.0
	v_fmac_f32_e32 v25, v29, v25
	v_div_scale_f32 v29, vcc, v5, v66, v5
	v_mul_f32_e32 v33, v29, v25
	v_fma_f32 v43, -v6, v33, v29
	v_fmac_f32_e32 v33, v43, v25
	v_fma_f32 v6, -v6, v33, v29
	v_div_fmas_f32 v6, v6, v25, v33
	v_div_fixup_f32 v66, v6, v66, v5
	v_lshlrev_b32_e32 v6, 16, v4
	v_and_b32_e32 v25, 0xffff0000, v4
	v_mul_f32_e32 v4, 0xbfb8aa3b, v6
	v_mul_f32_e32 v5, 0xbfb8aa3b, v25
	v_exp_f32_e32 v4, v4
	v_exp_f32_e32 v5, v5
	s_nop 0
	v_pk_add_f32 v[4:5], v[4:5], 1.0 op_sel_hi:[1,0]
	s_nop 0
	v_div_scale_f32 v29, s[6:7], v5, v5, v25
	v_rcp_f32_e32 v32, v29
	s_nop 0
	v_fma_f32 v33, -v29, v32, 1.0
	v_fmac_f32_e32 v32, v33, v32
	v_div_scale_f32 v33, vcc, v25, v5, v25
	v_mul_f32_e32 v43, v33, v32
	v_fma_f32 v47, -v29, v43, v33
	v_fmac_f32_e32 v43, v47, v32
	v_fma_f32 v29, -v29, v43, v33
	v_div_fmas_f32 v29, v29, v32, v43
	v_div_fixup_f32 v5, v29, v5, v25
	v_div_scale_f32 v25, s[6:7], v4, v4, v6
	v_rcp_f32_e32 v29, v25
	s_nop 0
	v_fma_f32 v32, -v25, v29, 1.0
	v_fmac_f32_e32 v29, v32, v29
	v_div_scale_f32 v32, vcc, v6, v4, v6
	v_mul_f32_e32 v33, v32, v29
	v_fma_f32 v43, -v25, v33, v32
	v_fmac_f32_e32 v33, v43, v29
	v_fma_f32 v25, -v25, v33, v32
	v_div_fmas_f32 v25, v25, v29, v33
	v_lshlrev_b32_e32 v29, 16, v28
	v_and_b32_e32 v28, 0xffff0000, v28
	v_div_fixup_f32 v4, v25, v4, v6
	v_lshlrev_b32_e32 v32, 16, v24
	v_and_b32_e32 v33, 0xffff0000, v24
	v_mul_f32_e32 v24, 0xbfb8aa3b, v29
	v_mul_f32_e32 v25, 0xbfb8aa3b, v28
	v_exp_f32_e32 v24, v24
	v_exp_f32_e32 v25, v25
	v_add_f32_e32 v6, 0, v32
	v_add_f32_e32 v6, v6, v33
	v_add_f32_e32 v6, v6, v68
	v_pk_add_f32 v[24:25], v[24:25], 1.0 op_sel_hi:[1,0]
	v_add_f32_e32 v6, v6, v69
	v_div_scale_f32 v43, s[6:7], v25, v25, v28
	v_rcp_f32_e32 v47, v43
	v_add_f32_e32 v6, v6, v62
	v_add_f32_e32 v6, v6, v63
	v_add_f32_e32 v6, v6, v58
	v_fma_f32 v49, -v43, v47, 1.0
	v_fmac_f32_e32 v47, v49, v47
	v_div_scale_f32 v49, vcc, v28, v25, v28
	v_mul_f32_e32 v76, v49, v47
	v_fma_f32 v77, -v43, v76, v49
	v_fmac_f32_e32 v76, v77, v47
	v_fma_f32 v43, -v43, v76, v49
	v_div_fmas_f32 v43, v43, v47, v76
	v_div_fixup_f32 v25, v43, v25, v28
	v_div_scale_f32 v28, s[6:7], v24, v24, v29
	v_rcp_f32_e32 v43, v28
	v_add_f32_e32 v6, v6, v59
	v_add_f32_e32 v6, v6, v70
	v_add_f32_e32 v6, v6, v71
	v_fma_f32 v47, -v28, v43, 1.0
	v_fmac_f32_e32 v43, v47, v43
	v_div_scale_f32 v47, vcc, v29, v24, v29
	v_add_f32_e32 v6, v6, v64
	v_mul_f32_e32 v49, v47, v43
	v_add_f32_e32 v6, v6, v65
	v_fma_f32 v76, -v28, v49, v47
	v_add_f32_e32 v6, v6, v60
	v_fmac_f32_e32 v49, v76, v43
	v_add_f32_e32 v6, v6, v61
	v_fma_f32 v28, -v28, v49, v47
	v_add_f32_e32 v6, v6, v56
	v_div_fmas_f32 v28, v28, v43, v49
	v_add_f32_e32 v6, v6, v57
	v_div_fixup_f32 v24, v28, v24, v29
	v_mov_b32_e32 v43, v3
	v_mov_b32_e32 v47, v3
	v_mov_b32_e32 v49, v3
	s_nop 1
	v_add_f32_dpp v6, v6, v6 quad_perm:[1,0,3,2] row_mask:0xf bank_mask:0xf
	s_nop 1
	v_add_f32_dpp v6, v6, v6 quad_perm:[2,3,0,1] row_mask:0xf bank_mask:0xf
	s_nop 1
	v_add_f32_dpp v6, v6, v6 row_half_mirror row_mask:0xf bank_mask:0xf
	s_nop 1
	v_add_f32_dpp v6, v6, v6 row_mirror row_mask:0xf bank_mask:0xf
	v_mul_f32_e32 v6, 0x3b800000, v6
	v_pk_add_f32 v[28:29], v[32:33], v[6:7] op_sel_hi:[1,0] neg_lo:[0,1] neg_hi:[0,1]
	v_pk_add_f32 v[68:69], v[68:69], v[6:7] op_sel_hi:[1,0] neg_lo:[0,1] neg_hi:[0,1]
	v_pk_mul_f32 v[32:33], v[28:29], v[28:29]
	v_pk_mul_f32 v[76:77], v[68:69], v[68:69]
	v_pk_add_f32 v[62:63], v[62:63], v[6:7] op_sel_hi:[1,0] neg_lo:[0,1] neg_hi:[0,1]
	v_pk_add_f32 v[58:59], v[58:59], v[6:7] op_sel_hi:[1,0] neg_lo:[0,1] neg_hi:[0,1]
	v_pk_add_f32 v[70:71], v[70:71], v[6:7] op_sel_hi:[1,0] neg_lo:[0,1] neg_hi:[0,1]
	v_pk_add_f32 v[64:65], v[64:65], v[6:7] op_sel_hi:[1,0] neg_lo:[0,1] neg_hi:[0,1]
	v_pk_add_f32 v[60:61], v[60:61], v[6:7] op_sel_hi:[1,0] neg_lo:[0,1] neg_hi:[0,1]
	v_pk_add_f32 v[56:57], v[56:57], v[6:7] op_sel_hi:[1,0] neg_lo:[0,1] neg_hi:[0,1]
	v_add_f32_e32 v6, v32, v33
	v_add_f32_e32 v6, v76, v6
	v_pk_mul_f32 v[78:79], v[62:63], v[62:63]
	v_add_f32_e32 v6, v77, v6
	v_add_f32_e32 v6, v78, v6
	v_pk_mul_f32 v[80:81], v[58:59], v[58:59]
	v_add_f32_e32 v6, v79, v6
	v_add_f32_e32 v6, v80, v6
; __device__ __forceinline__ unsigned cvt_pk_bf16(float lo, float hi) { const f32x2v v = {lo, hi}; const b16x2v r = __builtin_convertvector(v, b16x2v); return __builtin_bit_cast(unsigned, r); }
; __device__ __forceinline__ float bflo(unsigned u) { return __uint_as_float(u << 16); }
; __device__ __forceinline__ float fexp2(float x) { return __builtin_amdgcn_exp2f(x); }
; __device__ void merge_phase(const Params& p) {
;     ...
;           const float rstd = rsqrtf(q * (1.0f / 256.0f) + 1e-5f);
;           const bf16_t* rgp = h + (size_t)tok * HC + 2048 + hh * 256 + sub * 16;
;           const u32x4 ra = *(const u32x4*)rgp, rb = *(const u32x4*)(rgp + 8);
;           const float* ngp = p.norm_g + hh * 256 + sub * 16;
;           float ov[16];
; #pragma unroll
;           for (int j4 = 0; j4 < 4; ++j4) { const f32x4 ng = *(const f32x4*)(ngp + 4 * j4);
; #pragma unroll
;               for (int j = 0; j < 4; ++j) { const int e = 4 * j4 + j; const unsigned rw = (e < 8) ? ra[e >> 1] : rb[(e - 8) >> 1]; const float rv = (e & 1) ? bfhi(rw) : bflo(rw);
;                   ov[e] = (xv[e] - mean) * rstd * ng[j] * silu_f(rv); } }
;           u32x4 o0, o1;
; #pragma unroll
;           for (int j = 0; j < 4; ++j) { o0[j] = cvt_pk_bf16(ov[2 * j], ov[2 * j + 1]); o1[j] = cvt_pk_bf16(ov[8 + 2 * j], ov[8 + 2 * j + 1]); }
;           bf16_t* dst = mix + (size_t)tok * DM + hh * 256 + sub * 16;
;           *(u32x4*)dst = o0; *(u32x4*)(dst + 8) = o1; }
;         { const int hd = lane >> 3, sub = lane & 7;
;           const float l0 = lse[(size_t)tok * 8 + hd], l1 = lse[(size_t)T_TOK * 8 + (size_t)tok * 8 + hd], l2 = lse[(size_t)2 * T_TOK * 8 + (size_t)tok * 8 + hd];
;           const float m = fmaxf(l0, fmaxf(l1, l2));
;           float e0 = fexp2((l0 - m) * LOG2E), e1 = fexp2((l1 - m) * LOG2E), e2 = fexp2((l2 - m) * LOG2E);
;           const float inv = 1.0f / (e0 + e1 + e2); e0 *= inv; e1 *= inv; e2 *= inv;
;           const size_t so = (size_t)tok * 1024 + hd * 128 + sub * 16;
;           u32x4 o[2];
; #pragma unroll
;           for (int hf = 0; hf < 2; ++hf) { const u32x4 a = *(const u32x4*)(od0 + so + 8 * hf), b = *(const u32x4*)(od1 + so + 8 * hf), c = *(const u32x4*)(od2 + so + 8 * hf);
; #pragma unroll
;               for (int j = 0; j < 4; ++j) o[hf][j] = cvt_pk_bf16(e0 * bflo(a[j]) + e1 * bflo(b[j]) + e2 * bflo(c[j]), e0 * bfhi(a[j]) + e1 * bfhi(b[j]) + e2 * bfhi(c[j])); }
	v_pk_mul_f32 v[82:83], v[70:71], v[70:71]
	v_add_f32_e32 v6, v81, v6
	v_add_f32_e32 v6, v82, v6
	v_pk_mul_f32 v[84:85], v[64:65], v[64:65]
	v_add_f32_e32 v6, v83, v6
	v_add_f32_e32 v6, v84, v6
	v_pk_mul_f32 v[86:87], v[60:61], v[60:61]
	v_add_f32_e32 v6, v85, v6
	v_add_f32_e32 v6, v86, v6
	v_pk_mul_f32 v[88:89], v[56:57], v[56:57]
	v_add_f32_e32 v6, v87, v6
	v_add_f32_e32 v6, v88, v6
	v_add_f32_e32 v6, v89, v6
	s_nop 1
	v_add_f32_dpp v6, v6, v6 quad_perm:[1,0,3,2] row_mask:0xf bank_mask:0xf
	s_nop 1
	v_add_f32_dpp v6, v6, v6 quad_perm:[2,3,0,1] row_mask:0xf bank_mask:0xf
	s_nop 1
	v_add_f32_dpp v6, v6, v6 row_half_mirror row_mask:0xf bank_mask:0xf
	s_nop 1
	v_add_f32_dpp v6, v6, v6 row_mirror row_mask:0xf bank_mask:0xf
	v_fmamk_f32 v6, v6, 0x3b800000, v213
	v_cmp_gt_f32_e32 vcc, s15, v6
	v_mul_f32_e32 v32, 0x4b800000, v6
	s_nop 0
	v_cndmask_b32_e32 v6, v6, v32, vcc
	v_rsq_f32_e32 v6, v6
	s_nop 0
	v_mul_f32_e32 v32, 0x45800000, v6
	v_cndmask_b32_e32 v6, v6, v32, vcc
	v_pk_mul_f32 v[28:29], v[28:29], v[6:7] op_sel_hi:[1,0]
	s_nop 0
	v_pk_mul_f32 v[20:21], v[20:21], v[28:29]
	s_nop 0
	v_pk_mul_f32 v[20:21], v[24:25], v[20:21]
	v_pk_mul_f32 v[24:25], v[68:69], v[6:7] op_sel_hi:[1,0]
	s_nop 0
	v_pk_mul_f32 v[22:23], v[22:23], v[24:25]
	v_pk_mul_f32 v[24:25], v[62:63], v[6:7] op_sel_hi:[1,0]
	v_pk_mul_f32 v[22:23], v[66:67], v[22:23]
	v_pk_mul_f32 v[16:17], v[16:17], v[24:25]
	v_pk_mul_f32 v[24:25], v[58:59], v[6:7] op_sel_hi:[1,0]
	v_pk_mul_f32 v[16:17], v[26:27], v[16:17]
	v_pk_mul_f32 v[18:19], v[18:19], v[24:25]
	v_pk_mul_f32 v[24:25], v[70:71], v[6:7] op_sel_hi:[1,0]
	v_pk_mul_f32 v[18:19], v[54:55], v[18:19]
	v_pk_mul_f32 v[12:13], v[12:13], v[24:25]
	s_nop 0
	v_pk_mul_f32 v[12:13], v[4:5], v[12:13]
	v_pk_mul_f32 v[4:5], v[64:65], v[6:7] op_sel_hi:[1,0]
	s_nop 0
	v_pk_mul_f32 v[4:5], v[14:15], v[4:5]
	s_nop 0
	v_pk_mul_f32 v[14:15], v[30:31], v[4:5]
	v_pk_mul_f32 v[4:5], v[60:61], v[6:7] op_sel_hi:[1,0]
	s_nop 0
	v_pk_mul_f32 v[4:5], v[8:9], v[4:5]
	v_lshlrev_b32_e32 v8, 16, v7
	v_and_b32_e32 v9, 0xffff0000, v7
	v_pk_mul_f32 v[24:25], v[34:35], v[4:5]
	v_mul_f32_e32 v4, 0xbfb8aa3b, v8
	v_mul_f32_e32 v5, 0xbfb8aa3b, v9
	v_exp_f32_e32 v4, v4
	v_exp_f32_e32 v5, v5
	v_pk_mul_f32 v[6:7], v[56:57], v[6:7] op_sel_hi:[1,0]
	v_pk_add_f32 v[4:5], v[4:5], 1.0 op_sel_hi:[1,0]
	v_pk_mul_f32 v[6:7], v[10:11], v[6:7]
	v_div_scale_f32 v10, s[6:7], v5, v5, v9
	v_rcp_f32_e32 v11, v10
	s_nop 0
	v_fma_f32 v26, -v10, v11, 1.0
	v_fmac_f32_e32 v11, v26, v11
	v_div_scale_f32 v26, vcc, v9, v5, v9
	v_mul_f32_e32 v27, v26, v11
	v_fma_f32 v28, -v10, v27, v26
	v_fmac_f32_e32 v27, v28, v11
	v_fma_f32 v10, -v10, v27, v26
	v_div_fmas_f32 v10, v10, v11, v27
	v_div_fixup_f32 v5, v10, v5, v9
	v_div_scale_f32 v9, s[6:7], v4, v4, v8
	v_rcp_f32_e32 v10, v9
	s_mov_b32 s6, 0x100000
	v_fma_f32 v11, -v9, v10, 1.0
	v_fmac_f32_e32 v10, v11, v10
	v_div_scale_f32 v11, vcc, v8, v4, v8
	v_mul_f32_e32 v26, v11, v10
	v_fma_f32 v27, -v9, v26, v11
	v_fmac_f32_e32 v26, v27, v10
	v_fma_f32 v9, -v9, v26, v11
	v_div_fmas_f32 v9, v9, v10, v26
	v_div_fixup_f32 v4, v9, v4, v8
	v_cvt_pk_bf16_f32 v8, v12, v13
	v_lshlrev_b64 v[12:13], 13, v[0:1]
	v_sub_co_u32_e32 v12, vcc, 0, v12
	v_pk_mul_f32 v[26:27], v[4:5], v[6:7]
	s_nop 0
	v_subb_co_u32_e32 v13, vcc, 0, v13, vcc
	v_cvt_pk_bf16_f32 v6, v16, v17
	v_lshl_add_u64 v[16:17], v[52:53], 0, v[12:13]
	v_lshl_add_u64 v[12:13], v[16:17], 0, v[2:3]
	v_cvt_pk_bf16_f32 v4, v20, v21
	v_cvt_pk_bf16_f32 v5, v22, v23
	v_cvt_pk_bf16_f32 v7, v18, v19
	v_lshl_add_u64 v[12:13], v[12:13], 0, v[40:41]
	v_cvt_pk_bf16_f32 v9, v14, v15
	v_cvt_pk_bf16_f32 v10, v24, v25
	v_cvt_pk_bf16_f32 v11, v26, v27
	global_store_dwordx4 v[12:13], v[4:7], off
	global_store_dwordx4 v[12:13], v[8:11], off offset:16
	s_nop 0
	v_add_u32_e32 v0, s8, v0
	s_waitcnt vmcnt(8)
	v_mov_b32_e32 v1, v100
	v_mov_b32_e32 v6, v101
	v_mov_b32_e32 v4, v102
	v_max3_f32 v5, v1, v6, v4
	v_sub_f32_e32 v1, v1, v5
	v_mul_f32_e32 v1, 0x3fb8aa3b, v1
	v_exp_f32_e32 v21, v1
	v_sub_f32_e32 v1, v6, v5
	v_mul_f32_e32 v1, 0x3fb8aa3b, v1
	v_exp_f32_e32 v20, v1
	v_sub_f32_e32 v1, v4, v5
	v_mul_f32_e32 v1, 0x3fb8aa3b, v1
	v_exp_f32_e32 v1, v1
	v_add_f32_e32 v4, v21, v20
	v_add_f32_e32 v4, v1, v4
	v_div_scale_f32 v5, s[6:7], v4, v4, 1.0
	v_rcp_f32_e32 v6, v5
	s_nop 0
	v_fma_f32 v7, -v5, v6, 1.0
	v_fmac_f32_e32 v6, v7, v6
	v_div_scale_f32 v7, vcc, 1.0, v4, 1.0
	v_mul_f32_e32 v8, v7, v6
	v_fma_f32 v9, -v5, v8, v7
	v_fmac_f32_e32 v8, v9, v6
	v_fma_f32 v5, -v5, v8, v7
	v_div_fmas_f32 v5, v5, v6, v8
	v_div_fixup_f32 v22, v5, v4, 1.0
	v_mul_f32_e32 v18, v1, v22
	v_pk_mul_f32 v[50:51], v[20:21], v[22:23] op_sel_hi:[1,0]
	v_cmp_lt_i32_e32 vcc, s18, v0
	s_or_b64 s[2:3], vcc, s[2:3]
	s_waitcnt vmcnt(2)
; __device__ __forceinline__ unsigned cvt_pk_bf16(float lo, float hi) { const f32x2v v = {lo, hi}; const b16x2v r = __builtin_convertvector(v, b16x2v); return __builtin_bit_cast(unsigned, r); }
; __device__ __forceinline__ float bflo(unsigned u) { return __uint_as_float(u << 16); }
; __device__ __forceinline__ float bfhi(unsigned u) { return __uint_as_float(u & 0xffff0000u); }
; __device__ void merge_phase(const Params& p) {
;     ...
;           for (int hf = 0; hf < 2; ++hf) { const u32x4 a = *(const u32x4*)(od0 + so + 8 * hf), b = *(const u32x4*)(od1 + so + 8 * hf), c = *(const u32x4*)(od2 + so + 8 * hf);
; #pragma unroll
;               for (int j = 0; j < 4; ++j) o[hf][j] = cvt_pk_bf16(e0 * bflo(a[j]) + e1 * bflo(b[j]) + e2 * bflo(c[j]), e0 * bfhi(a[j]) + e1 * bfhi(b[j]) + e2 * bfhi(c[j])); }
;           bf16_t* dst = mix + (size_t)tok * DM + 1024 + hd * 128 + sub * 16;
;           *(u32x4*)dst = o[0]; *(u32x4*)(dst + 8) = o[1]; }
	v_mov_b64_e32 v[4:5], v[104:105]
	v_mov_b64_e32 v[6:7], v[106:107]
	v_mov_b64_e32 v[24:25], v[108:109]
	v_mov_b64_e32 v[26:27], v[110:111]
	v_mov_b64_e32 v[8:9], v[112:113]
	v_mov_b64_e32 v[10:11], v[114:115]
	v_mov_b64_e32 v[28:29], v[116:117]
	v_mov_b64_e32 v[30:31], v[118:119]
	v_mov_b64_e32 v[12:13], v[120:121]
	v_mov_b64_e32 v[14:15], v[122:123]
	v_mov_b64_e32 v[32:33], v[124:125]
	v_mov_b64_e32 v[34:35], v[126:127]
	v_lshlrev_b32_e32 v22, 16, v24
	v_and_b32_e32 v21, 0xffff0000, v24
	v_and_b32_e32 v23, 0xffff0000, v28
	v_lshlrev_b32_e32 v20, 16, v28
	v_pk_mul_f32 v[22:23], v[50:51], v[22:23] op_sel:[1,0] op_sel_hi:[0,1]
	v_pk_fma_f32 v[20:21], v[50:51], v[20:21], v[22:23]
	v_and_b32_e32 v23, 0xffff0000, v25
	v_lshlrev_b32_e32 v24, 16, v25
	v_and_b32_e32 v25, 0xffff0000, v29
	v_lshlrev_b32_e32 v22, 16, v29
	v_pk_mul_f32 v[24:25], v[50:51], v[24:25] op_sel:[1,0] op_sel_hi:[0,1]
	v_lshlrev_b32_e32 v52, 16, v32
	v_and_b32_e32 v53, 0xffff0000, v32
	v_lshlrev_b32_e32 v28, 16, v33
	v_and_b32_e32 v29, 0xffff0000, v33
	v_pk_fma_f32 v[22:23], v[50:51], v[22:23], v[24:25]
	v_pk_fma_f32 v[20:21], v[18:19], v[52:53], v[20:21] op_sel_hi:[0,1,1]
	v_pk_fma_f32 v[22:23], v[18:19], v[28:29], v[22:23] op_sel_hi:[0,1,1]
	v_lshlrev_b32_e32 v24, 16, v26
	v_and_b32_e32 v25, 0xffff0000, v30
	v_cvt_pk_bf16_f32 v20, v20, v21
	v_cvt_pk_bf16_f32 v21, v22, v23
	v_lshlrev_b32_e32 v22, 16, v30
	v_and_b32_e32 v23, 0xffff0000, v26
	v_pk_mul_f32 v[24:25], v[50:51], v[24:25] op_sel:[1,0] op_sel_hi:[0,1]
	v_pk_fma_f32 v[22:23], v[50:51], v[22:23], v[24:25]
	v_and_b32_e32 v25, 0xffff0000, v27
	v_lshlrev_b32_e32 v26, 16, v27
	v_and_b32_e32 v27, 0xffff0000, v31
	v_lshlrev_b32_e32 v28, 16, v34
	v_and_b32_e32 v29, 0xffff0000, v34
	v_lshlrev_b32_e32 v24, 16, v31
	v_pk_mul_f32 v[26:27], v[50:51], v[26:27] op_sel:[1,0] op_sel_hi:[0,1]
	v_pk_fma_f32 v[22:23], v[18:19], v[28:29], v[22:23] op_sel_hi:[0,1,1]
	v_lshlrev_b32_e32 v28, 16, v35
	v_and_b32_e32 v29, 0xffff0000, v35
	v_pk_fma_f32 v[24:25], v[50:51], v[24:25], v[26:27]
	v_lshlrev_b32_e32 v26, 16, v4
	v_pk_fma_f32 v[24:25], v[18:19], v[28:29], v[24:25] op_sel_hi:[0,1,1]
	v_and_b32_e32 v27, 0xffff0000, v8
	v_cvt_pk_bf16_f32 v22, v22, v23
	v_cvt_pk_bf16_f32 v23, v24, v25
	v_lshlrev_b32_e32 v24, 16, v8
	v_and_b32_e32 v25, 0xffff0000, v4
	v_pk_mul_f32 v[26:27], v[50:51], v[26:27] op_sel:[1,0] op_sel_hi:[0,1]
	v_lshlrev_b32_e32 v28, 16, v12
	v_and_b32_e32 v29, 0xffff0000, v12
	v_pk_fma_f32 v[24:25], v[50:51], v[24:25], v[26:27]
	v_lshlrev_b32_e32 v8, 16, v5
	v_pk_fma_f32 v[24:25], v[18:19], v[28:29], v[24:25] op_sel_hi:[0,1,1]
	v_cvt_pk_bf16_f32 v4, v24, v25
	v_lshlrev_b32_e32 v24, 16, v9
	v_and_b32_e32 v9, 0xffff0000, v9
	v_and_b32_e32 v25, 0xffff0000, v5
	v_pk_mul_f32 v[8:9], v[50:51], v[8:9] op_sel:[1,0] op_sel_hi:[0,1]
	v_lshlrev_b32_e32 v12, 16, v13
	v_and_b32_e32 v13, 0xffff0000, v13
	v_pk_fma_f32 v[8:9], v[50:51], v[24:25], v[8:9]
	v_lshlrev_b32_e32 v24, 16, v14
	v_pk_fma_f32 v[8:9], v[18:19], v[12:13], v[8:9] op_sel_hi:[0,1,1]
	v_lshlrev_b32_e32 v12, 16, v6
	v_and_b32_e32 v13, 0xffff0000, v10
	v_cvt_pk_bf16_f32 v5, v8, v9
	v_lshlrev_b32_e32 v8, 16, v10
	v_and_b32_e32 v9, 0xffff0000, v6
	v_pk_mul_f32 v[12:13], v[50:51], v[12:13] op_sel:[1,0] op_sel_hi:[0,1]
	v_and_b32_e32 v25, 0xffff0000, v14
	v_pk_fma_f32 v[8:9], v[50:51], v[8:9], v[12:13]
	v_lshlrev_b32_e32 v10, 16, v7
	v_pk_fma_f32 v[8:9], v[18:19], v[24:25], v[8:9] op_sel_hi:[0,1,1]
	v_cvt_pk_bf16_f32 v6, v8, v9
	v_lshlrev_b32_e32 v8, 16, v11
	v_and_b32_e32 v11, 0xffff0000, v11
	v_and_b32_e32 v9, 0xffff0000, v7
	v_pk_mul_f32 v[10:11], v[50:51], v[10:11] op_sel:[1,0] op_sel_hi:[0,1]
	v_pk_fma_f32 v[8:9], v[50:51], v[8:9], v[10:11]
	v_lshlrev_b32_e32 v10, 16, v15
	v_and_b32_e32 v11, 0xffff0000, v15
	v_pk_fma_f32 v[8:9], v[18:19], v[10:11], v[8:9] op_sel_hi:[0,1,1]
	v_cvt_pk_bf16_f32 v7, v8, v9
	v_lshl_add_u64 v[8:9], v[16:17], 0, v[46:47]
	v_lshl_add_u64 v[8:9], v[8:9], 0, v[48:49]
	global_store_dwordx4 v[8:9], v[20:23], off offset:2048
	global_store_dwordx4 v[8:9], v[4:7], off offset:2064
	s_andn2_b64 exec, exec, s[2:3]
	s_cbranch_execnz .LBB0_100
